# v82 + carry SLOC staging loads issued together (16 in flight)
# baseline (speedup 1.0000x reference)
.LBB0_264:
	s_xor_b64 s[56:57], s[58:59], -1
	s_or_b32 s58, s27, s19
	s_ashr_i32 s59, s58, 31
	s_lshl_b64 s[30:31], s[58:59], 9
	s_add_u32 s60, s20, s30
	s_addc_u32 s61, s18, s31
	global_load_dwordx4 v[156:159], v2, s[60:61]
	v_add_u32_e32 v132, 0x2000, v2
	v_add_u32_e32 v133, 0x6000, v2
	v_add_u32_e32 v134, 0xa000, v2
	v_add_u32_e32 v135, 0xe000, v2
	global_load_dwordx4 v[160:163], v132, s[60:61]
	global_load_dwordx4 v[164:167], v37, s[60:61]
	global_load_dwordx4 v[168:171], v133, s[60:61]
	global_load_dwordx4 v[172:175], v38, s[60:61]
	global_load_dwordx4 v[176:179], v134, s[60:61]
	global_load_dwordx4 v[180:183], v39, s[60:61]
	global_load_dwordx4 v[184:187], v135, s[60:61]
	v_add_u32_e32 v136, 0x12000, v2
	v_add_u32_e32 v137, 0x16000, v2
	v_add_u32_e32 v138, 0x1a000, v2
	v_add_u32_e32 v139, 0x1e000, v2
	global_load_dwordx4 v[188:191], v40, s[60:61]
	global_load_dwordx4 v[192:195], v136, s[60:61]
	global_load_dwordx4 v[196:199], v41, s[60:61]
	global_load_dwordx4 v[200:203], v137, s[60:61]
	global_load_dwordx4 v[204:207], v42, s[60:61]
	global_load_dwordx4 v[208:211], v138, s[60:61]
	global_load_dwordx4 v[212:215], v43, s[60:61]
	global_load_dwordx4 v[216:219], v139, s[60:61]
	v_lshl_add_u64 v[20:21], s[60:61], 0, v[2:3]
	v_mov_b32_e32 v22, 0
	s_mov_b32 s27, 0
	s_waitcnt vmcnt(15)
	ds_write_b128 v23, v[156:159]
	s_waitcnt vmcnt(14)
	ds_write_b128 v23, v[160:163] offset:8192
	s_waitcnt vmcnt(13)
	ds_write_b128 v23, v[164:167] offset:16384
	s_waitcnt vmcnt(12)
	ds_write_b128 v23, v[168:171] offset:24576
	s_waitcnt vmcnt(11)
	ds_write_b128 v23, v[172:175] offset:32768
	s_waitcnt vmcnt(10)
	ds_write_b128 v23, v[176:179] offset:40960
	s_waitcnt vmcnt(9)
	ds_write_b128 v23, v[180:183] offset:49152
	s_waitcnt vmcnt(8)
	ds_write_b128 v23, v[184:187] offset:57344
	s_waitcnt vmcnt(7)
	ds_write_b128 v25, v[188:191]
	s_waitcnt vmcnt(6)
	ds_write_b128 v26, v[192:195]
	s_waitcnt vmcnt(5)
	ds_write_b128 v27, v[196:199]
	s_waitcnt vmcnt(4)
	ds_write_b128 v28, v[200:203]
	s_waitcnt vmcnt(3)
	ds_write_b128 v29, v[204:207]
	s_waitcnt vmcnt(2)
	ds_write_b128 v30, v[208:211]
	s_waitcnt vmcnt(1)
	ds_write_b128 v31, v[212:215]
	s_waitcnt vmcnt(0)
	ds_write_b128 v32, v[216:219]
	v_mov_b32_e32 v20, 0
	s_waitcnt lgkmcnt(0)
	s_barrier
